# final-norm output written with default-policy stores
# baseline (speedup 1.0000x reference)
; __global__ void __launch_bounds__(NTHREADS, 2) mk_fwd(Args a) {
;     ...
;         for (int m = fn_first + wave; m < fn_end; m += fn_stride) {
;             const float rs = row_rstd(ss6, m);
; #pragma unroll
;             for (int p = 0; p < 2; ++p) {
;                 const u32x4 w = *(const u32x4*)(xb + (size_t)m * D + p * 512 + lane * 8);
;                 const f32x4 v0 = (f32x4){__uint_as_float(w.x << 16), __uint_as_float(w.x & 0xffff0000u), __uint_as_float(w.y << 16), __uint_as_float(w.y & 0xffff0000u)};
;                 const f32x4 v1 = (f32x4){__uint_as_float(w.z << 16), __uint_as_float(w.z & 0xffff0000u), __uint_as_float(w.w << 16), __uint_as_float(w.w & 0xffff0000u)};
;                 float* o = P.out + (size_t)m * D + p * 512 + lane * 8;
;                 __builtin_nontemporal_store(v0 * rs * gv[p][0], (f32x4*)o); __builtin_nontemporal_store(v1 * rs * gv[p][1], (f32x4*)(o + 4));
;             }
.LBB0_321:
	v_lshl_add_u64 v[32:33], s[88:89], 0, v[28:29]
	v_lshl_add_u64 v[34:35], s[88:89], 0, v[24:25]
	v_lshl_add_u64 v[52:53], v[32:33], 0, s[4:5]
	v_add_co_u32_e32 v54, vcc, 0xc00000, v32
	s_waitcnt vmcnt(0)
	v_add_co_u32_e64 v56, s[0:1], s8, v34
	v_addc_co_u32_e32 v55, vcc, 0, v33, vcc
	s_nop 0
	v_addc_co_u32_e64 v57, s[0:1], 0, v35, s[0:1]
	global_load_dwordx4 v[32:35], v[52:53], off offset:32
	global_load_dwordx4 v[36:39], v[52:53], off offset:16
	global_load_dwordx4 v[40:43], v[54:55], off
	global_load_dwordx4 v[44:47], v[52:53], off offset:48
	global_load_dwordx4 v[48:51], v[56:57], off
	v_add_u32_e32 v17, v17, v16
	v_lshl_add_u64 v[28:29], v[28:29], 0, v[18:19]
	v_lshl_add_u64 v[24:25], v[24:25], 0, v[26:27]
	s_waitcnt vmcnt(2)
	v_pk_add_f32 v[38:39], v[42:43], v[38:39]
	v_pk_add_f32 v[36:37], v[40:41], v[36:37]
	s_waitcnt vmcnt(1)
	v_pk_add_f32 v[34:35], v[34:35], v[46:47]
	v_pk_add_f32 v[32:33], v[32:33], v[44:45]
	v_pk_add_f32 v[34:35], v[38:39], v[34:35]
	v_pk_add_f32 v[32:33], v[36:37], v[32:33]
	s_waitcnt vmcnt(0)
	v_lshlrev_b32_e32 v52, 16, v48
	v_pk_mov_b32 v[36:37], v[32:33], v[34:35] op_sel:[1,0]
	v_mov_b32_e32 v33, v35
	v_pk_add_f32 v[32:33], v[36:37], v[32:33]
	v_and_b32_e32 v53, 0xffff0000, v48
	v_add_f32_e32 v31, v32, v33
	v_fmamk_f32 v31, v31, 0x3a800000, v30
	v_mul_f32_e32 v32, 0x4b800000, v31
	v_cmp_gt_f32_e32 vcc, s7, v31
	v_lshlrev_b32_e32 v48, 16, v49
	v_and_b32_e32 v49, 0xffff0000, v49
	v_cndmask_b32_e32 v31, v31, v32, vcc
	v_rsq_f32_e32 v31, v31
	v_lshlrev_b32_e32 v54, 16, v50
	v_and_b32_e32 v55, 0xffff0000, v50
	v_lshlrev_b32_e32 v50, 16, v51
	v_mul_f32_e32 v32, 0x45800000, v31
	v_cndmask_b32_e32 v40, v31, v32, vcc
	v_and_b32_e32 v51, 0xffff0000, v51
	v_pk_mul_f32 v[32:33], v[40:41], v[52:53] op_sel_hi:[0,1]
	v_pk_mul_f32 v[34:35], v[40:41], v[48:49] op_sel_hi:[0,1]
	v_pk_mul_f32 v[36:37], v[40:41], v[54:55] op_sel_hi:[0,1]
	v_pk_mul_f32 v[38:39], v[40:41], v[50:51] op_sel_hi:[0,1]
	v_pk_mul_f32 v[34:35], v[6:7], v[34:35]
	v_pk_mul_f32 v[32:33], v[4:5], v[32:33]
	v_pk_mul_f32 v[38:39], v[2:3], v[38:39]
	v_pk_mul_f32 v[36:37], v[0:1], v[36:37]
	global_store_dwordx4 v[20:21], v[32:35], off offset:-2064
	global_store_dwordx4 v[20:21], v[36:39], off offset:-2048
	global_load_dwordx4 v[32:35], v[56:57], off offset:1024
	v_cmp_le_i32_e32 vcc, s6, v17
	s_or_b64 s[2:3], vcc, s[2:3]
	s_waitcnt vmcnt(0)
	v_lshlrev_b32_e32 v36, 16, v32
	v_and_b32_e32 v37, 0xffff0000, v32
	v_lshlrev_b32_e32 v32, 16, v33
	v_and_b32_e32 v33, 0xffff0000, v33
	v_lshlrev_b32_e32 v38, 16, v34
	v_and_b32_e32 v39, 0xffff0000, v34
	v_lshlrev_b32_e32 v34, 16, v35
	v_and_b32_e32 v35, 0xffff0000, v35
	v_pk_mul_f32 v[36:37], v[40:41], v[36:37] op_sel_hi:[0,1]
	v_pk_mul_f32 v[32:33], v[40:41], v[32:33] op_sel_hi:[0,1]
	v_pk_mul_f32 v[42:43], v[40:41], v[38:39] op_sel_hi:[0,1]
	v_pk_mul_f32 v[38:39], v[40:41], v[34:35] op_sel_hi:[0,1]
	v_pk_mul_f32 v[34:35], v[14:15], v[32:33]
	v_pk_mul_f32 v[32:33], v[12:13], v[36:37]
	v_pk_mul_f32 v[38:39], v[10:11], v[38:39]
	v_pk_mul_f32 v[36:37], v[8:9], v[42:43]
	global_store_dwordx4 v[20:21], v[32:35], off offset:-16
	global_store_dwordx4 v[20:21], v[36:39], off
	v_lshl_add_u64 v[20:21], v[20:21], 0, v[22:23]
	s_andn2_b64 exec, exec, s[2:3]
	s_cbranch_execnz .LBB0_321
